# P0 row loop: per-row log-sigmoid (8 useful lanes, ~115 VALU per row) replaced by one 64-lane log-sigmoid pass after the wave's 8 rows; rows park their 8 logits in lane 8k+slot
# speedup vs baseline: 1.0036x; 1.0036x over previous
.LBB0_110:
	v_lshlrev_b32_e32 v80, 12, v223
	s_add_i32 s0, 0, 0x18000
	v_and_b32_e32 v80, 0x7000, v80
	v_add_u32_e32 v80, s0, v80
	s_waitcnt vmcnt(14)
	v_mul_f32_e32 v64, v137, v172
	v_lshl_add_u32 v81, v135, 2, v80
	v_mul_f32_e32 v65, v139, v140
	ds_write_b32 v81, v64
	v_lshl_add_u32 v64, v136, 2, v80
	s_waitcnt vmcnt(13)
	v_mul_f32_e32 v66, v142, v171
	v_mul_f32_e32 v67, v143, v144
	ds_write_b32 v64, v65
	ds_write_b32 v81, v66 offset:512
	v_lshl_add_u32 v64, v138, 2, v80
	s_waitcnt vmcnt(12)
	v_mul_f32_e32 v68, v146, v170
	v_mul_f32_e32 v69, v147, v148
	ds_write_b32 v64, v67
	ds_write_b32 v81, v68 offset:1024
	v_lshl_add_u32 v64, v141, 2, v80
	s_waitcnt vmcnt(11)
	v_mul_f32_e32 v70, v150, v169
	v_mul_f32_e32 v71, v151, v152
	ds_write_b32 v64, v69
	ds_write_b32 v81, v70 offset:1536
	v_lshl_add_u32 v64, v145, 2, v80
	s_waitcnt vmcnt(10)
	v_mul_f32_e32 v72, v154, v167
	v_mul_f32_e32 v73, v155, v156
	ds_write_b32 v64, v71
	ds_write_b32 v81, v72 offset:2048
	v_lshl_add_u32 v64, v149, 2, v80
	s_waitcnt vmcnt(9)
	v_mul_f32_e32 v74, v158, v166
	v_mul_f32_e32 v75, v159, v160
	ds_write_b32 v64, v73
	ds_write_b32 v81, v74 offset:2560
	v_lshl_add_u32 v64, v153, 2, v80
	s_waitcnt vmcnt(8)
	v_mul_f32_e32 v76, v162, v165
	v_mul_f32_e32 v77, v163, v164
	ds_write_b32 v64, v75
	ds_write_b32 v81, v76 offset:3072
	v_lshl_add_u32 v64, v157, 2, v80
	s_waitcnt vmcnt(6)
	v_mul_f32_e32 v78, v173, v168
	s_waitcnt vmcnt(4)
	v_mul_f32_e32 v79, v174, v175
	ds_write_b32 v64, v77
	ds_write_b32 v81, v78 offset:3584
	v_lshl_add_u32 v64, v161, 2, v80
	s_and_b64 vcc, exec, s[10:11]
	v_lshlrev_b32_e32 v210, 3, v224
	ds_write_b32 v64, v79
	s_waitcnt lgkmcnt(0)
	s_barrier
	s_cbranch_vccz .LBB0_117
	v_mbcnt_lo_u32_b32 v64, -1, 0
	v_mbcnt_hi_u32_b32 v64, -1, v64
	v_and_b32_e32 v65, 64, v64
	v_add_u32_e32 v65, 64, v65
	v_xor_b32_e32 v66, 1, v64
	v_cmp_lt_i32_e32 vcc, v66, v65
	v_mov_b32_e32 v209, 0
	v_readlane_b32 s8, v252, 8
	v_cndmask_b32_e32 v66, v64, v66, vcc
	v_lshlrev_b32_e32 v225, 2, v66
	v_xor_b32_e32 v66, 2, v64
	v_cmp_lt_i32_e32 vcc, v66, v65
	v_readlane_b32 s16, v252, 16
	v_readlane_b32 s17, v252, 17
	v_cndmask_b32_e32 v66, v64, v66, vcc
	v_lshlrev_b32_e32 v226, 2, v66
	v_xor_b32_e32 v66, 4, v64
	v_cmp_lt_i32_e32 vcc, v66, v65
	s_mov_b64 s[0:1], 0x2700000
	v_readlane_b32 s9, v252, 9
	v_cndmask_b32_e32 v66, v64, v66, vcc
	v_lshlrev_b32_e32 v227, 2, v66
	v_xor_b32_e32 v66, 8, v64
	v_cmp_lt_i32_e32 vcc, v66, v65
	v_readlane_b32 s10, v252, 10
	v_readlane_b32 s11, v252, 11
	v_cndmask_b32_e32 v66, v64, v66, vcc
	v_lshlrev_b32_e32 v228, 2, v66
	v_xor_b32_e32 v66, 16, v64
	v_cmp_lt_i32_e32 vcc, v66, v65
	v_readlane_b32 s12, v252, 12
	v_readlane_b32 s13, v252, 13
	v_cndmask_b32_e32 v66, v64, v66, vcc
	v_lshlrev_b32_e32 v229, 2, v66
	v_xor_b32_e32 v66, 32, v64
	v_cmp_lt_i32_e32 vcc, v66, v65
	v_mov_b32_e32 v65, v209
	v_readlane_b32 s14, v252, 14
	v_cndmask_b32_e32 v64, v64, v66, vcc
	v_lshlrev_b32_e32 v230, 2, v64
	v_add_u32_e32 v64, 0, v208
	v_add_u32_e32 v188, 0x18000, v64
	v_bfe_u32 v64, v224, 4, 1
	v_bfe_u32 v66, v224, 5, 1
	v_lshl_add_u32 v64, v64, 1, v66
	v_bfe_u32 v66, v224, 3, 1
	v_lshl_add_u32 v64, v66, 2, v64
	v_lshlrev_b32_e32 v64, 2, v64
	v_lshl_add_u64 v[216:217], s[16:17], 0, v[64:65]
	v_and_b32_e32 v226, 28, v64
	v_mov_b32_e32 v227, 0
	v_lshl_add_u64 v[226:227], s[16:17], 0, v[226:227]
	global_load_dword v225, v[226:227], off
	v_lshl_add_u64 v[64:65], s[30:31], 0, v[64:65]
	v_lshl_add_u64 v[218:219], v[64:65], 0, s[0:1]
	ds_read_b128 v[64:67], v188
	ds_read_b128 v[68:71], v188 offset:1024
	ds_read_b128 v[72:75], v188 offset:2048
	ds_read_b128 v[76:79], v188 offset:3072
	ds_read_b128 v[80:83], v188 offset:4096
	ds_read_b128 v[84:87], v188 offset:5120
	ds_read_b128 v[88:91], v188 offset:6144
	ds_read_b128 v[92:95], v188 offset:7168
	ds_read_b128 v[96:99], v188 offset:8192
	ds_read_b128 v[100:103], v188 offset:9216
	ds_read_b128 v[104:107], v188 offset:10240
	ds_read_b128 v[108:111], v188 offset:11264
	ds_read_b128 v[112:115], v188 offset:12288
	ds_read_b128 v[116:119], v188 offset:13312
	ds_read_b128 v[120:123], v188 offset:14336
	ds_read_b128 v[124:127], v188 offset:15360
	ds_read_b128 v[128:131], v188 offset:16384
	ds_read_b128 v[132:135], v188 offset:17408
	ds_read_b128 v[136:139], v188 offset:18432
	ds_read_b128 v[140:143], v188 offset:19456
	ds_read_b128 v[144:147], v188 offset:20480
	ds_read_b128 v[148:151], v188 offset:21504
	ds_read_b128 v[152:155], v188 offset:22528
	ds_read_b128 v[156:159], v188 offset:23552
	ds_read_b128 v[160:163], v188 offset:24576
	ds_read_b128 v[164:167], v188 offset:25600
	ds_read_b128 v[168:171], v188 offset:26624
	ds_read_b128 v[172:175], v188 offset:27648
	ds_read_b128 v[176:179], v188 offset:28672
	ds_read_b128 v[180:183], v188 offset:29696
	ds_read_b128 v[184:187], v188 offset:30720
	ds_read_b128 v[188:191], v188 offset:31744
	v_readlane_b32 s15, v252, 15
	v_readlane_b32 s18, v252, 18
	v_readlane_b32 s19, v252, 19
	v_readlane_b32 s20, v252, 20
	v_readlane_b32 s21, v252, 21
	v_readlane_b32 s22, v252, 22
	v_readlane_b32 s23, v252, 23
	v_mov_b32_e32 v211, v209
	s_lshl_b32 s3, s26, 4
	v_lshl_add_u64 v[212:213], s[8:9], 0, v[208:209]
	v_lshl_add_u64 v[214:215], s[24:25], 0, v[210:211]
	v_and_b32_e32 v229, 7, v224
	v_cmp_eq_u32_e32 vcc, 0, v229
	v_cmp_eq_u32_e64 s[8:9], 0, v224
	v_cmp_eq_u32_e64 s[10:11], 1, v224
	v_cmp_eq_u32_e64 s[12:13], 2, v224
	v_cmp_eq_u32_e64 s[14:15], 3, v224
	v_cmp_eq_u32_e64 s[16:17], 4, v224
	v_cmp_eq_u32_e64 s[18:19], 5, v224
	v_cmp_eq_u32_e64 s[20:21], 6, v224
	v_cmp_eq_u32_e64 s[22:23], 7, v224
	v_mov_b32_e32 v209, 0x358637bd
	s_mov_b32 s27, 0x800000
	s_mov_b32 s35, 0xbfb8aa3b
	s_mov_b32 s41, 0x3f2aaaab
	v_mov_b32_e32 v211, 0x3ecc95a3
	s_mov_b32 s52, 0x3f317218
	s_mov_b32 s53, 0x7f800000
	s_mov_b32 s54, 0x33800000
	v_mov_b32_e32 v220, 0x3f317218
	v_mov_b32_e32 v231, 0x7f800000
	v_mov_b32_e32 v232, 0x7fc00000
	v_mov_b32_e32 v233, 0xff800000
	s_mov_b32 s68, s86
	v_mov_b32_e32 v230, 0
	s_mov_b32 s8, 0x1010101
	s_mov_b32 s9, 0x1010101
	s_waitcnt vmcnt(0)
	s_branch .LBB0_113
.LBB0_112:
	s_sub_i32 s68, s44, s84
	v_mov_b64_e32 v[60:61], v[204:205]
	v_mov_b64_e32 v[56:57], v[200:201]
	v_mov_b64_e32 v[52:53], v[196:197]
	v_mov_b64_e32 v[48:49], v[192:193]
	s_cmpk_gt_i32 s68, 0x3fff
	v_mov_b64_e32 v[62:63], v[206:207]
	v_mov_b64_e32 v[58:59], v[202:203]
	v_mov_b64_e32 v[54:55], v[198:199]
	v_mov_b64_e32 v[50:51], v[194:195]
	s_cbranch_scc1 rowfin_0
	s_waitcnt vmcnt(4)

.LBB0_115:
	s_waitcnt lgkmcnt(0)
	v_pk_mul_f32 v[226:227], v[60:61], v[60:61]
	v_pk_fma_f32 v[226:227], v[62:63], v[62:63], v[226:227]
	v_pk_fma_f32 v[226:227], v[56:57], v[56:57], v[226:227]
	v_pk_fma_f32 v[226:227], v[58:59], v[58:59], v[226:227]
	v_pk_fma_f32 v[226:227], v[52:53], v[52:53], v[226:227]
	v_pk_fma_f32 v[226:227], v[54:55], v[54:55], v[226:227]
	v_pk_fma_f32 v[226:227], v[48:49], v[48:49], v[226:227]
	v_pk_fma_f32 v[226:227], v[50:51], v[50:51], v[226:227]
	v_add_f32_e32 v221, v226, v227
	v_pk_mul_f32 v[234:235], v[60:61], v[64:65]
	v_pk_fma_f32 v[234:235], v[62:63], v[66:67], v[234:235]
	v_add_f32_dpp v221, v221, v221 quad_perm:[1,0,3,2] row_mask:0xf bank_mask:0xf
	v_pk_fma_f32 v[234:235], v[56:57], v[68:69], v[234:235]
	v_pk_fma_f32 v[234:235], v[58:59], v[70:71], v[234:235]
	v_pk_fma_f32 v[234:235], v[52:53], v[72:73], v[234:235]
	v_add_f32_dpp v221, v221, v221 quad_perm:[2,3,0,1] row_mask:0xf bank_mask:0xf
	v_pk_fma_f32 v[234:235], v[54:55], v[74:75], v[234:235]
	v_pk_fma_f32 v[234:235], v[48:49], v[76:77], v[234:235]
	v_pk_fma_f32 v[234:235], v[50:51], v[78:79], v[234:235]
	v_add_f32_dpp v221, v221, v221 row_half_mirror row_mask:0xf bank_mask:0xf
	v_add_f32_e32 v234, v234, v235
	v_pk_mul_f32 v[236:237], v[60:61], v[80:81]
	v_pk_fma_f32 v[236:237], v[62:63], v[82:83], v[236:237]
	v_add_f32_dpp v221, v221, v221 row_mirror row_mask:0xf bank_mask:0xf
	v_pk_fma_f32 v[236:237], v[56:57], v[84:85], v[236:237]
	v_pk_fma_f32 v[236:237], v[58:59], v[86:87], v[236:237]
	v_pk_fma_f32 v[236:237], v[52:53], v[88:89], v[236:237]
	v_mov_b32_e32 v222, v221
	v_pk_fma_f32 v[236:237], v[54:55], v[90:91], v[236:237]
	v_pk_fma_f32 v[236:237], v[48:49], v[92:93], v[236:237]
	v_pk_fma_f32 v[236:237], v[50:51], v[94:95], v[236:237]
	v_permlane16_swap_b32_e32 v222, v221
	v_add_f32_e32 v236, v236, v237
	v_pk_mul_f32 v[238:239], v[60:61], v[96:97]
	v_pk_fma_f32 v[238:239], v[62:63], v[98:99], v[238:239]
	v_add_f32_e32 v221, v221, v222
	v_pk_fma_f32 v[238:239], v[56:57], v[100:101], v[238:239]
	v_pk_fma_f32 v[238:239], v[58:59], v[102:103], v[238:239]
	v_pk_fma_f32 v[238:239], v[52:53], v[104:105], v[238:239]
	v_mov_b32_e32 v222, v221
	v_pk_fma_f32 v[238:239], v[54:55], v[106:107], v[238:239]
	v_pk_fma_f32 v[238:239], v[48:49], v[108:109], v[238:239]
	v_pk_fma_f32 v[238:239], v[50:51], v[110:111], v[238:239]
	v_permlane32_swap_b32_e32 v222, v221
	v_add_f32_e32 v238, v238, v239
	v_pk_mul_f32 v[240:241], v[60:61], v[112:113]
	v_pk_fma_f32 v[240:241], v[62:63], v[114:115], v[240:241]
	v_add_f32_e32 v221, v221, v222
	v_pk_fma_f32 v[240:241], v[56:57], v[116:117], v[240:241]
	v_pk_fma_f32 v[240:241], v[58:59], v[118:119], v[240:241]
	v_pk_fma_f32 v[240:241], v[52:53], v[120:121], v[240:241]
	v_fmamk_f32 v221, v221, 0x3a800000, v209
	v_pk_fma_f32 v[240:241], v[54:55], v[122:123], v[240:241]
	v_pk_fma_f32 v[240:241], v[48:49], v[124:125], v[240:241]
	v_pk_fma_f32 v[240:241], v[50:51], v[126:127], v[240:241]
	v_cmp_gt_f32_e64 s[0:1], s27, v221
	v_add_f32_e32 v240, v240, v241
	v_pk_mul_f32 v[242:243], v[60:61], v[128:129]
	v_pk_fma_f32 v[242:243], v[62:63], v[130:131], v[242:243]
	v_mul_f32_e32 v228, 0x4b800000, v221
	v_pk_fma_f32 v[242:243], v[56:57], v[132:133], v[242:243]
	v_pk_fma_f32 v[242:243], v[58:59], v[134:135], v[242:243]
	v_pk_fma_f32 v[242:243], v[52:53], v[136:137], v[242:243]
	v_cndmask_b32_e64 v221, v221, v228, s[0:1]
	v_pk_fma_f32 v[242:243], v[54:55], v[138:139], v[242:243]
	v_pk_fma_f32 v[242:243], v[48:49], v[140:141], v[242:243]
	v_pk_fma_f32 v[242:243], v[50:51], v[142:143], v[242:243]
	v_rsq_f32_e32 v221, v221
	v_add_f32_e32 v242, v242, v243
	v_pk_mul_f32 v[244:245], v[60:61], v[144:145]
	v_pk_fma_f32 v[244:245], v[62:63], v[146:147], v[244:245]
	v_mul_f32_e32 v222, 0x45800000, v221
	v_pk_fma_f32 v[244:245], v[56:57], v[148:149], v[244:245]
	v_pk_fma_f32 v[244:245], v[58:59], v[150:151], v[244:245]
	v_pk_fma_f32 v[244:245], v[52:53], v[152:153], v[244:245]
	v_cndmask_b32_e64 v222, v221, v222, s[0:1]
	v_pk_fma_f32 v[244:245], v[54:55], v[154:155], v[244:245]
	v_pk_fma_f32 v[244:245], v[48:49], v[156:157], v[244:245]
	v_pk_fma_f32 v[244:245], v[50:51], v[158:159], v[244:245]
	v_add_f32_e32 v244, v244, v245
	v_pk_mul_f32 v[246:247], v[60:61], v[160:161]
	v_pk_fma_f32 v[246:247], v[62:63], v[162:163], v[246:247]
	v_pk_fma_f32 v[246:247], v[56:57], v[164:165], v[246:247]
	v_pk_fma_f32 v[246:247], v[58:59], v[166:167], v[246:247]
	v_pk_fma_f32 v[246:247], v[52:53], v[168:169], v[246:247]
	v_pk_fma_f32 v[246:247], v[54:55], v[170:171], v[246:247]
	v_pk_fma_f32 v[246:247], v[48:49], v[172:173], v[246:247]
	v_pk_fma_f32 v[246:247], v[50:51], v[174:175], v[246:247]
	v_add_f32_e32 v246, v246, v247
	v_pk_mul_f32 v[248:249], v[60:61], v[176:177]
	v_pk_fma_f32 v[248:249], v[62:63], v[178:179], v[248:249]
	v_pk_fma_f32 v[248:249], v[56:57], v[180:181], v[248:249]
	v_pk_fma_f32 v[248:249], v[58:59], v[182:183], v[248:249]
	v_pk_fma_f32 v[248:249], v[52:53], v[184:185], v[248:249]
	v_pk_fma_f32 v[248:249], v[54:55], v[186:187], v[248:249]
	v_pk_fma_f32 v[248:249], v[48:49], v[188:189], v[248:249]
	v_pk_fma_f32 v[248:249], v[50:51], v[190:191], v[248:249]
	v_add_f32_e32 v248, v248, v249
	v_permlane32_swap_b32_e32 v234, v236
	v_permlane32_swap_b32_e32 v238, v240
	v_permlane32_swap_b32_e32 v242, v244
	v_permlane32_swap_b32_e32 v246, v248
	v_add_f32_e32 v234, v234, v236
	v_add_f32_e32 v238, v238, v240
	v_add_f32_e32 v242, v242, v244
	v_add_f32_e32 v246, v246, v248
	v_permlane16_swap_b32_e32 v234, v238
	s_nop 0
	v_permlane16_swap_b32_e32 v242, v246
	v_add_f32_e32 v234, v234, v238
	v_add_f32_e32 v242, v242, v246
	s_ashr_i32 s69, s68, 31
	v_pk_mul_f32 v[62:63], v[18:19], v[62:63]
	v_add_f32_dpp v229, v234, v234 row_ror:8 row_mask:0xf bank_mask:0x3
	v_pk_mul_f32 v[60:61], v[16:17], v[60:61]
	v_pk_mul_f32 v[58:59], v[22:23], v[58:59]
	v_pk_mul_f32 v[56:57], v[20:21], v[56:57]
	v_add_f32_dpp v229, v242, v242 row_ror:8 row_mask:0xf bank_mask:0xc
	v_pk_mul_f32 v[54:55], v[26:27], v[54:55]
	v_pk_mul_f32 v[52:53], v[24:25], v[52:53]
	v_pk_mul_f32 v[50:51], v[30:31], v[50:51]
	v_add_f32_dpp v229, v229, v229 row_half_mirror row_mask:0xf bank_mask:0xf
	v_pk_mul_f32 v[48:49], v[28:29], v[48:49]
	s_lshl_b64 s[0:1], s[68:69], 11
	v_pk_mul_f32 v[62:63], v[62:63], v[222:223] op_sel_hi:[1,0]
	v_add_f32_dpp v229, v229, v229 quad_perm:[2,3,0,1] row_mask:0xf bank_mask:0xf
	v_pk_mul_f32 v[60:61], v[60:61], v[222:223] op_sel_hi:[1,0]
	v_pk_mul_f32 v[58:59], v[58:59], v[222:223] op_sel_hi:[1,0]
	v_pk_mul_f32 v[56:57], v[56:57], v[222:223] op_sel_hi:[1,0]
	v_add_f32_dpp v229, v229, v229 quad_perm:[1,0,3,2] row_mask:0xf bank_mask:0xf
	v_pk_mul_f32 v[54:55], v[54:55], v[222:223] op_sel_hi:[1,0]
	v_pk_mul_f32 v[52:53], v[52:53], v[222:223] op_sel_hi:[1,0]
	v_pk_mul_f32 v[50:51], v[50:51], v[222:223] op_sel_hi:[1,0]
	v_pk_mul_f32 v[48:49], v[48:49], v[222:223] op_sel_hi:[1,0]
	v_lshl_add_u64 v[250:251], v[214:215], 0, s[0:1]
	v_cvt_pk_bf16_f32 v60, v60, v61
	v_cvt_pk_bf16_f32 v61, v62, v63
	v_cvt_pk_bf16_f32 v56, v56, v57
	v_cvt_pk_bf16_f32 v57, v58, v59
	v_cvt_pk_bf16_f32 v52, v52, v53
	v_cvt_pk_bf16_f32 v53, v54, v55
	v_cvt_pk_bf16_f32 v48, v48, v49
	v_cvt_pk_bf16_f32 v49, v50, v51
	global_store_dwordx2 v[250:251], v[60:61], off
	global_store_dwordx2 v[250:251], v[56:57], off offset:512
	global_store_dwordx2 v[250:251], v[52:53], off offset:1024
	global_store_dwordx2 v[250:251], v[48:49], off offset:1536
	v_mul_f32_e32 v49, v222, v229
	v_cndmask_b32_e64 v230, v230, v49, s[8:9]
	s_lshl_b64 s[8:9], s[8:9], 1
	s_branch .LBB0_112
rowfin_0:
	v_and_b32_e32 v226, 7, v224
	v_mul_lo_u32 v226, v226, s84
	v_add_u32_e32 v226, s86, v226
	v_cmp_gt_u32_e32 vcc, 0x4000, v226
	v_lshlrev_b32_e32 v226, 5, v226
	v_mov_b32_e32 v227, 0
	v_lshl_add_u64 v[226:227], v[218:219], 0, v[226:227]
	s_and_saveexec_b64 s[70:71], vcc
	v_add_f32_e32 v48, v230, v225
	v_mul_f32_e64 v49, |v48|, s35
	v_exp_f32_e32 v62, v49
	v_min_f32_e32 v63, 0, v48
	v_add_f32_e32 v50, 1.0, v62
	v_add_f32_e32 v51, -1.0, v50
	v_frexp_mant_f32_e32 v52, v50
	v_cvt_f64_f32_e32 v[48:49], v50
	v_sub_f32_e32 v53, v51, v50
	v_frexp_exp_i32_f64_e32 v48, v[48:49]
	v_cmp_gt_f32_e64 s[0:1], s41, v52
	v_sub_f32_e32 v51, v62, v51
	v_add_f32_e32 v49, 1.0, v53
	v_subbrev_co_u32_e64 v48, s[0:1], 0, v48, s[0:1]
	v_add_f32_e32 v49, v51, v49
	v_sub_u32_e32 v51, 0, v48
	v_ldexp_f32 v50, v50, v51
	v_add_f32_e32 v52, -1.0, v50
	v_add_f32_e32 v53, 1.0, v50
	v_ldexp_f32 v49, v49, v51
	v_add_f32_e32 v51, 1.0, v52
	v_add_f32_e32 v54, -1.0, v53
	v_sub_f32_e32 v51, v50, v51
	v_sub_f32_e32 v50, v50, v54
	v_add_f32_e32 v54, v49, v51
	v_add_f32_e32 v49, v49, v50
	v_add_f32_e32 v56, v53, v49
	v_rcp_f32_e32 v57, v56
	v_add_f32_e32 v51, v52, v54
	v_sub_f32_e32 v52, v51, v52
	v_sub_f32_e32 v50, v56, v53
	v_mul_f32_e32 v59, v51, v57
	v_sub_f32_e32 v58, v54, v52
	v_mul_f32_e32 v52, v56, v59
	v_sub_f32_e32 v49, v49, v50
	v_fma_f32 v54, v59, v56, -v52
	v_fmac_f32_e32 v54, v59, v49
	v_add_f32_e32 v50, v52, v54
	v_sub_f32_e32 v53, v51, v50
	v_mov_b32_e32 v55, v50
	v_pk_add_f32 v[50:51], v[50:51], v[52:53] neg_lo:[0,1] neg_hi:[0,1]
	v_cvt_f32_i32_e32 v48, v48
	v_pk_add_f32 v[50:51], v[50:51], v[54:55] neg_lo:[0,1] neg_hi:[0,1]
	v_cmp_neq_f32_e64 s[0:1], s53, v62
	v_add_f32_e32 v51, v58, v51
	v_add_f32_e32 v50, v50, v51
	v_add_f32_e32 v51, v53, v50
	v_mul_f32_e32 v55, v57, v51
	v_mul_f32_e32 v52, v56, v55
	v_sub_f32_e32 v53, v53, v51
	v_add_f32_e32 v60, v59, v55
	v_fma_f32 v54, v55, v56, -v52
	v_add_f32_e32 v58, v50, v53
	v_sub_f32_e32 v50, v60, v59
	v_fmac_f32_e32 v54, v55, v49
	v_sub_f32_e32 v49, v55, v50
	v_add_f32_e32 v50, v52, v54
	v_sub_f32_e32 v53, v51, v50
	v_mov_b32_e32 v55, v50
	v_pk_add_f32 v[50:51], v[50:51], v[52:53] neg_lo:[0,1] neg_hi:[0,1]
	s_nop 0
	v_pk_add_f32 v[50:51], v[50:51], v[54:55] neg_lo:[0,1] neg_hi:[0,1]
	s_nop 0
	v_add_f32_e32 v51, v58, v51
	v_add_f32_e32 v50, v50, v51
	v_add_f32_e32 v50, v53, v50
	v_mul_f32_e32 v50, v57, v50
	v_add_f32_e32 v49, v49, v50
	v_add_f32_e32 v50, v60, v49
	v_mul_f32_e32 v52, v50, v50
	v_sub_f32_e32 v53, v50, v60
	v_fmamk_f32 v54, v52, 0x3e9b6dac, v211
	v_sub_f32_e32 v53, v49, v53
	v_mul_f32_e32 v49, v50, v52
	v_fmaak_f32 v221, v52, v54, 0x3f2aaada
	v_ldexp_f32 v55, v53, 1
	v_pk_mul_f32 v[52:53], v[48:49], v[220:221]
	v_ldexp_f32 v51, v50, 1
	v_fma_f32 v50, v48, s52, -v52
	v_fmac_f32_e32 v50, 0xb102e308, v48
	v_pk_add_f32 v[48:49], v[52:53], v[50:51]
	v_mov_b32_e32 v54, v52
	v_sub_f32_e32 v58, v49, v51
	v_pk_add_f32 v[56:57], v[48:49], v[52:53] neg_lo:[0,1] neg_hi:[0,1]
	v_sub_f32_e32 v52, v53, v58
	v_add_f32_e32 v55, v55, v52
	v_pk_add_f32 v[52:53], v[48:49], v[54:55]
	v_mov_b32_e32 v51, v48
	v_mov_b32_e32 v57, v53
	v_pk_add_f32 v[60:61], v[50:51], v[56:57] neg_lo:[0,1] neg_hi:[0,1]
	v_pk_add_f32 v[50:51], v[50:51], v[56:57]
	v_mov_b32_e32 v59, v48
	v_pk_add_f32 v[56:57], v[50:51], v[48:49] op_sel:[1,0] op_sel_hi:[0,1] neg_lo:[0,1] neg_hi:[0,1]
	v_mov_b32_e32 v58, v55
	v_mov_b32_e32 v54, v53
	v_mov_b32_e32 v55, v51
	v_pk_mov_b32 v[48:49], v[48:49], v[56:57] op_sel:[1,0]
	v_pk_add_f32 v[52:53], v[52:53], v[56:57] op_sel_hi:[1,0] neg_lo:[0,1] neg_hi:[0,1]
	v_pk_add_f32 v[48:49], v[54:55], v[48:49] neg_lo:[0,1] neg_hi:[0,1]
	v_mov_b32_e32 v52, v60
	v_pk_add_f32 v[48:49], v[58:59], v[48:49] neg_lo:[0,1] neg_hi:[0,1]
	v_mov_b32_e32 v61, v51
	v_pk_add_f32 v[52:53], v[52:53], v[48:49]
	s_nop 0
	v_pk_add_f32 v[54:55], v[52:53], v[52:53] op_sel:[0,1] op_sel_hi:[1,0]
	s_nop 0
	v_pk_add_f32 v[50:51], v[50:51], v[54:55] op_sel:[1,0] op_sel_hi:[0,1]
	v_mov_b32_e32 v53, v50
	v_mov_b32_e32 v49, v54
	v_pk_add_f32 v[54:55], v[52:53], v[60:61] neg_lo:[0,1] neg_hi:[0,1]
	s_nop 0
	v_sub_f32_e32 v51, v52, v54
	v_pk_add_f32 v[48:49], v[48:49], v[54:55] neg_lo:[0,1] neg_hi:[0,1]
	v_sub_f32_e32 v51, v60, v51
	v_add_f32_e32 v48, v48, v51
	v_add_f32_e32 v48, v48, v49
	v_add_f32_e32 v48, v50, v48
	v_cndmask_b32_e64 v48, v231, v48, s[0:1]
	v_cmp_ngt_f32_e64 s[0:1], -1.0, v62
	s_nop 1
	v_cndmask_b32_e64 v48, v232, v48, s[0:1]
	v_cmp_neq_f32_e64 s[0:1], -1.0, v62
	s_nop 1
	v_cndmask_b32_e64 v48, v233, v48, s[0:1]
	v_cmp_lt_f32_e64 s[0:1], |v62|, s54
	s_nop 1
	v_cndmask_b32_e64 v48, v48, v62, s[0:1]
	v_sub_f32_e32 v50, v63, v48
	global_store_dword v[226:227], v50, off
	s_or_b64 exec, exec, s[70:71]
